# remainder-strip 128x128 K-loops of the three big-tile GEMM phases software-pipelined (fragment double buffer), constants restored after each
# baseline (speedup 1.0000x reference)
.Lxk_184:
	ds_read_b128 v[230:233], v137
	ds_read_b128 v[234:237], v137 offset:2048
	ds_read_b128 v[238:241], v137 offset:4096
	ds_read_b128 v[242:245], v137 offset:6144
	ds_read_b128 v[246:249], v138 offset:16384
	ds_read_b128 v[194:197], v138 offset:18432
	ds_read_b128 v[198:201], v138 offset:20480
	ds_read_b128 v[202:205], v138 offset:22528
	s_waitcnt lgkmcnt(8)
	v_mfma_f32_16x16x32_bf16 v[124:127], v[156:159], v[140:143], v[124:127]
	s_add_i32 s4, s4, 2
	v_mfma_f32_16x16x32_bf16 v[108:111], v[160:163], v[140:143], v[108:111]
	s_min_u32 s5, s4, 12
	v_mfma_f32_16x16x32_bf16 v[56:59], v[164:167], v[140:143], v[56:59]
	s_lshl_b32 s56, s5, 7
	v_mfma_f32_16x16x32_bf16 v[12:15], v[168:171], v[140:143], v[12:15]
	s_min_u32 s5, s4, 11
	s_waitcnt vmcnt(15)
	v_mfma_f32_16x16x32_bf16 v[120:123], v[156:159], v[144:147], v[120:123]
	ds_write_b128 v134, v[20:23] offset:32768
	v_mfma_f32_16x16x32_bf16 v[100:103], v[160:163], v[144:147], v[100:103]
	s_waitcnt vmcnt(14)
	v_mfma_f32_16x16x32_bf16 v[48:51], v[164:167], v[144:147], v[48:51]
	ds_write_b128 v134, v[24:27] offset:49152
	v_mfma_f32_16x16x32_bf16 v[8:11], v[168:171], v[144:147], v[8:11]
	s_waitcnt vmcnt(13)
	ds_write_b128 v134, v[28:31] offset:36864
	v_mfma_f32_16x16x32_bf16 v[116:119], v[156:159], v[148:151], v[116:119]
	s_waitcnt vmcnt(12)
	v_mfma_f32_16x16x32_bf16 v[92:95], v[160:163], v[148:151], v[92:95]
	ds_write_b128 v134, v[36:39] offset:53248
	v_mfma_f32_16x16x32_bf16 v[32:35], v[164:167], v[148:151], v[32:35]
	s_waitcnt vmcnt(11)
	v_mfma_f32_16x16x32_bf16 v[4:7], v[168:171], v[148:151], v[4:7]
	ds_write_b128 v134, v[40:43] offset:40960
	s_waitcnt vmcnt(10)
	v_mfma_f32_16x16x32_bf16 v[112:115], v[156:159], v[152:155], v[112:115]
	ds_write_b128 v134, v[44:47] offset:57344
	v_mfma_f32_16x16x32_bf16 v[84:87], v[160:163], v[152:155], v[84:87]
	s_waitcnt vmcnt(9)
	v_mfma_f32_16x16x32_bf16 v[16:19], v[164:167], v[152:155], v[16:19]
	ds_write_b128 v134, v[52:55] offset:45056
	v_mfma_f32_16x16x32_bf16 v[0:3], v[168:171], v[152:155], v[0:3]
	s_waitcnt vmcnt(8)
	ds_write_b128 v134, v[60:63] offset:61440
	s_waitcnt lgkmcnt(0)
	s_barrier
	ds_read_b128 v[140:143], v135 offset:32768
	ds_read_b128 v[144:147], v135 offset:34816
	ds_read_b128 v[148:151], v135 offset:36864
	ds_read_b128 v[152:155], v135 offset:38912
	ds_read_b128 v[156:159], v136 offset:49152
	ds_read_b128 v[160:163], v136 offset:51200
	ds_read_b128 v[164:167], v136 offset:53248
	ds_read_b128 v[168:171], v136 offset:55296
	v_mfma_f32_16x16x32_bf16 v[124:127], v[246:249], v[230:233], v[124:127]
	v_lshl_add_u64 v[52:53], v[130:131], 0, s[56:57]
	v_mfma_f32_16x16x32_bf16 v[108:111], v[194:197], v[230:233], v[108:111]
	v_add_co_u32_e32 v28, vcc, s65, v52
	v_lshl_add_u64 v[60:61], v[132:133], 0, s[56:57]
	v_mfma_f32_16x16x32_bf16 v[56:59], v[198:201], v[230:233], v[56:59]
	s_nop 0
	v_mfma_f32_16x16x32_bf16 v[12:15], v[202:205], v[230:233], v[12:15]
	v_addc_co_u32_e32 v29, vcc, 0, v53, vcc
	v_add_co_u32_e32 v36, vcc, s65, v60
	v_mfma_f32_16x16x32_bf16 v[120:123], v[246:249], v[234:237], v[120:123]
	global_load_dwordx4 v[20:23], v[52:53], off offset:384
	v_mfma_f32_16x16x32_bf16 v[100:103], v[194:197], v[234:237], v[100:103]
	global_load_dwordx4 v[24:27], v[60:61], off offset:384
	v_addc_co_u32_e32 v37, vcc, 0, v61, vcc
	v_mfma_f32_16x16x32_bf16 v[48:51], v[198:201], v[234:237], v[48:51]
	v_add_co_u32_e32 v40, vcc, s46, v52
	v_mfma_f32_16x16x32_bf16 v[8:11], v[202:205], v[234:237], v[8:11]
	s_nop 0
	v_addc_co_u32_e32 v41, vcc, 0, v53, vcc
	v_add_co_u32_e32 v44, vcc, s46, v60
	v_mfma_f32_16x16x32_bf16 v[116:119], v[246:249], v[238:241], v[116:119]
	s_nop 0
	v_addc_co_u32_e32 v45, vcc, 0, v61, vcc
	v_add_co_u32_e32 v52, vcc, s47, v52
	v_mfma_f32_16x16x32_bf16 v[92:95], v[194:197], v[238:241], v[92:95]
	s_nop 0
	v_addc_co_u32_e32 v53, vcc, 0, v53, vcc
	v_mfma_f32_16x16x32_bf16 v[32:35], v[198:201], v[238:241], v[32:35]
	v_add_co_u32_e32 v60, vcc, s47, v60
	s_nop 1
	v_addc_co_u32_e32 v61, vcc, 0, v61, vcc
	v_mfma_f32_16x16x32_bf16 v[4:7], v[202:205], v[238:241], v[4:7]
	global_load_dwordx4 v[28:31], v[28:29], off offset:384
	v_mfma_f32_16x16x32_bf16 v[112:115], v[246:249], v[242:245], v[112:115]
	global_load_dwordx4 v[36:39], v[36:37], off offset:384
	s_lshl_b32 s56, s5, 7
	v_mfma_f32_16x16x32_bf16 v[84:87], v[194:197], v[242:245], v[84:87]
	global_load_dwordx4 v[40:43], v[40:41], off offset:384
	v_mfma_f32_16x16x32_bf16 v[16:19], v[198:201], v[242:245], v[16:19]
	global_load_dwordx4 v[44:47], v[44:45], off offset:384
	s_cmp_lt_u32 s4, 14
	v_mfma_f32_16x16x32_bf16 v[0:3], v[202:205], v[242:245], v[0:3]
	global_load_dwordx4 v[52:55], v[52:53], off offset:384
	global_load_dwordx4 v[60:63], v[60:61], off offset:384
	ds_read_b128 v[230:233], v137 offset:32768
	ds_read_b128 v[234:237], v137 offset:34816
	ds_read_b128 v[238:241], v137 offset:36864
	ds_read_b128 v[242:245], v137 offset:38912
	ds_read_b128 v[246:249], v138 offset:49152
	ds_read_b128 v[194:197], v138 offset:51200
	ds_read_b128 v[198:201], v138 offset:53248
	ds_read_b128 v[202:205], v138 offset:55296
	s_waitcnt lgkmcnt(8)
	v_mfma_f32_16x16x32_bf16 v[124:127], v[156:159], v[140:143], v[124:127]
	s_waitcnt vmcnt(15)
	v_mfma_f32_16x16x32_bf16 v[108:111], v[160:163], v[140:143], v[108:111]
	ds_write_b128 v134, v[64:67]
	v_mfma_f32_16x16x32_bf16 v[56:59], v[164:167], v[140:143], v[56:59]
	s_waitcnt vmcnt(14)
	v_mfma_f32_16x16x32_bf16 v[12:15], v[168:171], v[140:143], v[12:15]
	ds_write_b128 v134, v[68:71] offset:16384
	v_mfma_f32_16x16x32_bf16 v[120:123], v[156:159], v[144:147], v[120:123]
	s_waitcnt vmcnt(13)
	v_mfma_f32_16x16x32_bf16 v[100:103], v[160:163], v[144:147], v[100:103]
	ds_write_b128 v134, v[72:75] offset:4096
	v_mfma_f32_16x16x32_bf16 v[48:51], v[164:167], v[144:147], v[48:51]
	s_waitcnt vmcnt(12)
	v_mfma_f32_16x16x32_bf16 v[8:11], v[168:171], v[144:147], v[8:11]
	ds_write_b128 v134, v[76:79] offset:20480
	v_mfma_f32_16x16x32_bf16 v[116:119], v[156:159], v[148:151], v[116:119]
	s_waitcnt vmcnt(11)
	v_mfma_f32_16x16x32_bf16 v[92:95], v[160:163], v[148:151], v[92:95]
	ds_write_b128 v134, v[80:83] offset:8192
	v_mfma_f32_16x16x32_bf16 v[32:35], v[164:167], v[148:151], v[32:35]
	s_waitcnt vmcnt(10)
	v_mfma_f32_16x16x32_bf16 v[4:7], v[168:171], v[148:151], v[4:7]
	ds_write_b128 v134, v[88:91] offset:24576
	v_mfma_f32_16x16x32_bf16 v[112:115], v[156:159], v[152:155], v[112:115]
	s_waitcnt vmcnt(9)
	v_mfma_f32_16x16x32_bf16 v[84:87], v[160:163], v[152:155], v[84:87]
	ds_write_b128 v134, v[96:99] offset:12288
	v_mfma_f32_16x16x32_bf16 v[16:19], v[164:167], v[152:155], v[16:19]
	s_waitcnt vmcnt(8)
	v_mfma_f32_16x16x32_bf16 v[0:3], v[168:171], v[152:155], v[0:3]
	ds_write_b128 v134, v[104:107] offset:28672
	s_waitcnt lgkmcnt(0)
	s_barrier
	ds_read_b128 v[140:143], v135
	ds_read_b128 v[144:147], v135 offset:2048
	ds_read_b128 v[148:151], v135 offset:4096
	ds_read_b128 v[152:155], v135 offset:6144
	ds_read_b128 v[156:159], v136 offset:16384
	ds_read_b128 v[160:163], v136 offset:18432
	ds_read_b128 v[164:167], v136 offset:20480
	ds_read_b128 v[168:171], v136 offset:22528
	v_mfma_f32_16x16x32_bf16 v[124:127], v[246:249], v[230:233], v[124:127]
	v_lshl_add_u64 v[96:97], v[130:131], 0, s[56:57]
	v_mfma_f32_16x16x32_bf16 v[108:111], v[194:197], v[230:233], v[108:111]
	v_add_co_u32_e32 v72, vcc, s65, v96
	v_lshl_add_u64 v[104:105], v[132:133], 0, s[56:57]
	v_mfma_f32_16x16x32_bf16 v[56:59], v[198:201], v[230:233], v[56:59]
	s_nop 0
	v_addc_co_u32_e32 v73, vcc, 0, v97, vcc
	v_mfma_f32_16x16x32_bf16 v[12:15], v[202:205], v[230:233], v[12:15]
	v_add_co_u32_e32 v76, vcc, s65, v104
	v_mfma_f32_16x16x32_bf16 v[120:123], v[246:249], v[234:237], v[120:123]
	global_load_dwordx4 v[64:67], v[96:97], off offset:512
	global_load_dwordx4 v[68:71], v[104:105], off offset:512
	v_mfma_f32_16x16x32_bf16 v[100:103], v[194:197], v[234:237], v[100:103]
	v_addc_co_u32_e32 v77, vcc, 0, v105, vcc
	v_add_co_u32_e32 v80, vcc, s46, v96
	v_mfma_f32_16x16x32_bf16 v[48:51], v[198:201], v[234:237], v[48:51]
	global_load_dwordx4 v[72:75], v[72:73], off offset:512
	v_mfma_f32_16x16x32_bf16 v[8:11], v[202:205], v[234:237], v[8:11]
	s_nop 0
	v_addc_co_u32_e32 v81, vcc, 0, v97, vcc
	v_mfma_f32_16x16x32_bf16 v[116:119], v[246:249], v[238:241], v[116:119]
	v_add_co_u32_e32 v88, vcc, s46, v104
	global_load_dwordx4 v[76:79], v[76:77], off offset:512
	v_mfma_f32_16x16x32_bf16 v[92:95], v[194:197], v[238:241], v[92:95]
	s_nop 0
	v_mfma_f32_16x16x32_bf16 v[32:35], v[198:201], v[238:241], v[32:35]
	v_addc_co_u32_e32 v89, vcc, 0, v105, vcc
	v_add_co_u32_e32 v96, vcc, s47, v96
	v_mfma_f32_16x16x32_bf16 v[4:7], v[202:205], v[238:241], v[4:7]
	global_load_dwordx4 v[80:83], v[80:81], off offset:512
	s_nop 0
	v_mfma_f32_16x16x32_bf16 v[112:115], v[246:249], v[242:245], v[112:115]
	v_addc_co_u32_e32 v97, vcc, 0, v97, vcc
	v_mfma_f32_16x16x32_bf16 v[84:87], v[194:197], v[242:245], v[84:87]
	v_add_co_u32_e32 v104, vcc, s47, v104
	global_load_dwordx4 v[88:91], v[88:89], off offset:512
	v_mfma_f32_16x16x32_bf16 v[16:19], v[198:201], v[242:245], v[16:19]
	s_nop 0
	v_addc_co_u32_e32 v105, vcc, 0, v105, vcc
	v_mfma_f32_16x16x32_bf16 v[0:3], v[202:205], v[242:245], v[0:3]
	global_load_dwordx4 v[96:99], v[96:97], off offset:512
	global_load_dwordx4 v[104:107], v[104:105], off offset:512
	s_cbranch_scc1 .Lxk_184
	s_waitcnt vmcnt(0) lgkmcnt(0)
	v_mov_b32_e32 v194, 0x11004
	v_mov_b32_e32 v195, 1
	v_mov_b32_e32 v196, 0x3727c5ac
	v_mov_b32_e32 v197, 0x260
	v_mov_b32_e32 v198, -1
	v_mbcnt_lo_u32_b32 v199, -1, 0
	v_mbcnt_hi_u32_b32 v199, -1, v199
	v_and_b32_e32 v200, 64, v199
	v_add_u32_e32 v201, 64, v200
	v_xor_b32_e32 v202, 32, v199
	v_xor_b32_e32 v203, 16, v199
	v_xor_b32_e32 v204, 8, v199
	v_xor_b32_e32 v205, 4, v199
	s_waitcnt vmcnt(15)
	v_mov_b32_e32 v20, v192
	s_lshl_b32 s4, s6, 7
	s_waitcnt vmcnt(10)
	v_and_b32_e32 v46, 64, v20
	v_lshrrev_b32_e32 v20, 2, v20
	v_and_b32_e32 v20, 12, v20
	v_or3_b32 v20, s4, v20, v46
	v_ashrrev_i32_e32 v21, 31, v20
	v_lshl_add_u64 v[44:45], v[20:21], 2, s[0:1]
	global_load_dwordx4 v[52:55], v[44:45], off offset:128
	global_load_dwordx4 v[26:29], v[44:45], off
	global_load_dwordx4 v[38:41], v[44:45], off offset:64
	s_ashr_i32 s5, s4, 31
	v_lshlrev_b32_e32 v176, 1, v46
	s_add_i32 s6, s6, s8
	s_cmp_gt_i32 s6, 31
	s_waitcnt vmcnt(2)
	v_pk_add_f32 v[34:35], v[34:35], v[54:55]
	v_pk_add_f32 v[32:33], v[32:33], v[52:53]
	v_pk_add_f32 v[18:19], v[18:19], v[54:55]
	v_pk_add_f32 v[16:17], v[16:17], v[52:53]
	v_max_f32_e32 v32, 0, v32
	v_max_f32_e32 v33, 0, v33
	v_max_f32_e32 v34, 0, v34
	v_max_f32_e32 v35, 0, v35
	v_max_f32_e32 v16, 0, v16
	v_max_f32_e32 v17, 0, v17
	v_max_f32_e32 v18, 0, v18
	v_max_f32_e32 v19, 0, v19
	v_mul_f32_e32 v32, v32, v32
	v_mul_f32_e32 v33, v33, v33
	v_mul_f32_e32 v34, v34, v34
	v_mul_f32_e32 v35, v35, v35
	v_mul_f32_e32 v16, v16, v16
	v_mul_f32_e32 v17, v17, v17
	v_mul_f32_e32 v18, v18, v18
	v_mul_f32_e32 v19, v19, v19
	s_nop 1
	v_cvt_pk_bf16_f32 v32, v32, v33
	s_nop 1
	v_cvt_pk_bf16_f32 v33, v34, v35
	s_nop 1
	v_cvt_pk_bf16_f32 v34, v16, v17
	s_nop 1
	v_cvt_pk_bf16_f32 v35, v18, v19
	global_load_dwordx4 v[16:19], v[44:45], off offset:192
	s_waitcnt vmcnt(2)
	v_pk_add_f32 v[20:21], v[126:127], v[28:29]
	v_pk_add_f32 v[22:23], v[124:125], v[26:27]
	v_max_f32_e32 v20, 0, v20
	v_max_f32_e32 v22, 0, v22
	v_max_f32_e32 v23, 0, v23
	v_mul_f32_e32 v22, v22, v22
	v_mul_f32_e32 v23, v23, v23
	v_mul_f32_e32 v24, v20, v20
	v_max_f32_e32 v20, 0, v21
	v_mul_f32_e32 v21, v20, v20
	s_nop 1
	v_cvt_pk_bf16_f32 v20, v22, v23
	v_pk_add_f32 v[22:23], v[122:123], v[28:29]
	s_nop 1
	v_cvt_pk_bf16_f32 v21, v24, v21
	v_pk_add_f32 v[24:25], v[120:121], v[26:27]
	v_max_f32_e32 v22, 0, v22
	v_max_f32_e32 v24, 0, v24
	v_max_f32_e32 v25, 0, v25
	v_mul_f32_e32 v30, v22, v22
	v_max_f32_e32 v22, 0, v23
	v_mul_f32_e32 v24, v24, v24
	v_mul_f32_e32 v25, v25, v25
	v_mul_f32_e32 v23, v22, v22
	s_nop 1
	v_cvt_pk_bf16_f32 v22, v24, v25
	s_nop 1
	v_cvt_pk_bf16_f32 v23, v30, v23
	v_pk_add_f32 v[24:25], v[118:119], v[28:29]
	v_pk_add_f32 v[30:31], v[116:117], v[26:27]
	v_pk_add_f32 v[28:29], v[114:115], v[28:29]
	v_pk_add_f32 v[26:27], v[112:113], v[26:27]
	v_max_f32_e32 v30, 0, v30
	v_max_f32_e32 v31, 0, v31
	v_max_f32_e32 v24, 0, v24
	v_max_f32_e32 v26, 0, v26
	v_max_f32_e32 v27, 0, v27
	v_max_f32_e32 v28, 0, v28
	v_max_f32_e32 v29, 0, v29
	v_mul_f32_e32 v30, v30, v30
	v_mul_f32_e32 v31, v31, v31
	v_mul_f32_e32 v36, v24, v24
	v_max_f32_e32 v24, 0, v25
	v_mul_f32_e32 v26, v26, v26
	v_mul_f32_e32 v27, v27, v27
	v_mul_f32_e32 v28, v28, v28
	v_mul_f32_e32 v29, v29, v29
	v_mul_f32_e32 v25, v24, v24
	s_nop 1
	v_cvt_pk_bf16_f32 v24, v30, v31
	s_nop 1
	v_cvt_pk_bf16_f32 v26, v26, v27
	s_nop 1
	v_cvt_pk_bf16_f32 v27, v28, v29
	s_waitcnt vmcnt(1)
	v_pk_add_f32 v[28:29], v[110:111], v[40:41]
	v_pk_add_f32 v[30:31], v[108:109], v[38:39]
	v_max_f32_e32 v28, 0, v28
	v_max_f32_e32 v30, 0, v30
	v_max_f32_e32 v31, 0, v31
	s_nop 1
	v_cvt_pk_bf16_f32 v25, v36, v25
	v_mul_f32_e32 v30, v30, v30
	v_mul_f32_e32 v31, v31, v31
	v_mul_f32_e32 v36, v28, v28
	v_max_f32_e32 v28, 0, v29
	v_mul_f32_e32 v29, v28, v28
	s_nop 1
	v_cvt_pk_bf16_f32 v28, v30, v31
	v_pk_add_f32 v[30:31], v[102:103], v[40:41]
	s_nop 1
	v_cvt_pk_bf16_f32 v29, v36, v29
	v_pk_add_f32 v[36:37], v[100:101], v[38:39]
	v_max_f32_e32 v30, 0, v30
	v_max_f32_e32 v36, 0, v36
	v_max_f32_e32 v37, 0, v37
	v_mul_f32_e32 v42, v30, v30
	v_max_f32_e32 v30, 0, v31
	v_mul_f32_e32 v36, v36, v36
	v_mul_f32_e32 v37, v37, v37
	v_mul_f32_e32 v31, v30, v30
	s_nop 1
	v_cvt_pk_bf16_f32 v30, v36, v37
	s_nop 1
	v_cvt_pk_bf16_f32 v31, v42, v31
	v_pk_add_f32 v[36:37], v[94:95], v[40:41]
	v_pk_add_f32 v[42:43], v[92:93], v[38:39]
	v_pk_add_f32 v[40:41], v[86:87], v[40:41]
	v_pk_add_f32 v[38:39], v[84:85], v[38:39]
	v_max_f32_e32 v42, 0, v42
	v_max_f32_e32 v43, 0, v43
	v_max_f32_e32 v36, 0, v36
	v_max_f32_e32 v38, 0, v38
	v_max_f32_e32 v39, 0, v39
	v_max_f32_e32 v40, 0, v40
	v_max_f32_e32 v41, 0, v41
	v_mul_f32_e32 v42, v42, v42
	v_mul_f32_e32 v43, v43, v43
	v_mul_f32_e32 v47, v36, v36
	v_max_f32_e32 v36, 0, v37
	v_mul_f32_e32 v38, v38, v38
	v_mul_f32_e32 v39, v39, v39
	v_mul_f32_e32 v40, v40, v40
	v_mul_f32_e32 v41, v41, v41
	s_waitcnt vmcnt(0)
	v_pk_add_f32 v[10:11], v[10:11], v[18:19]
	v_pk_add_f32 v[8:9], v[8:9], v[16:17]
	v_mul_f32_e32 v37, v36, v36
	s_nop 1
	v_cvt_pk_bf16_f32 v36, v42, v43
	s_nop 1
	v_cvt_pk_bf16_f32 v38, v38, v39
	s_nop 1
	v_cvt_pk_bf16_f32 v39, v40, v41
	v_pk_add_f32 v[40:41], v[58:59], v[54:55]
	v_pk_add_f32 v[42:43], v[56:57], v[52:53]
	v_max_f32_e32 v8, 0, v8
	v_max_f32_e32 v9, 0, v9
	v_max_f32_e32 v10, 0, v10
	v_max_f32_e32 v42, 0, v42
	v_max_f32_e32 v43, 0, v43
	v_max_f32_e32 v40, 0, v40
	v_mul_f32_e32 v8, v8, v8
	v_mul_f32_e32 v9, v9, v9
	v_mul_f32_e32 v10, v10, v10
	v_max_f32_e32 v11, 0, v11
	v_pk_add_f32 v[6:7], v[6:7], v[18:19]
	v_pk_add_f32 v[4:5], v[4:5], v[16:17]
	s_nop 1
	v_cvt_pk_bf16_f32 v37, v47, v37
	v_mul_f32_e32 v42, v42, v42
	v_mul_f32_e32 v43, v43, v43
	v_mul_f32_e32 v47, v40, v40
	v_max_f32_e32 v40, 0, v41
	v_pk_add_f32 v[14:15], v[14:15], v[18:19]
	v_pk_add_f32 v[12:13], v[12:13], v[16:17]
	v_mul_f32_e32 v11, v11, v11
	s_nop 1
	v_cvt_pk_bf16_f32 v8, v8, v9
	s_nop 1
	v_cvt_pk_bf16_f32 v9, v10, v11
	v_max_f32_e32 v4, 0, v4
	v_max_f32_e32 v5, 0, v5
	v_max_f32_e32 v6, 0, v6
	v_max_f32_e32 v7, 0, v7
	v_mov_b32_e32 v10, v192
	v_mul_f32_e32 v41, v40, v40
	s_nop 1
	v_cvt_pk_bf16_f32 v40, v42, v43
	v_pk_add_f32 v[42:43], v[50:51], v[54:55]
	v_max_f32_e32 v12, 0, v12
	v_max_f32_e32 v13, 0, v13
	v_max_f32_e32 v14, 0, v14
	v_max_f32_e32 v15, 0, v15
	v_mul_f32_e32 v4, v4, v4
	v_mul_f32_e32 v5, v5, v5
	v_mul_f32_e32 v6, v6, v6
	v_mul_f32_e32 v7, v7, v7
	v_pk_add_f32 v[48:49], v[48:49], v[52:53]
	v_lshlrev_b32_e32 v11, 7, v10
	v_max_f32_e32 v42, 0, v42
	v_mul_f32_e32 v12, v12, v12
	v_mul_f32_e32 v13, v13, v13
	v_mul_f32_e32 v14, v14, v14
	v_mul_f32_e32 v15, v15, v15
	s_nop 1
	v_cvt_pk_bf16_f32 v4, v4, v5
	s_nop 1
	v_cvt_pk_bf16_f32 v5, v6, v7
	v_pk_add_f32 v[2:3], v[2:3], v[18:19]
	v_pk_add_f32 v[0:1], v[0:1], v[16:17]
	v_and_b32_e32 v6, 15, v10
	v_bfe_u32 v7, v10, 4, 2
	v_and_b32_e32 v11, 0xffffe000, v11
	s_nop 1
	v_cvt_pk_bf16_f32 v41, v47, v41
	v_max_f32_e32 v47, 0, v48
	v_max_f32_e32 v48, 0, v49
	v_mul_f32_e32 v49, v42, v42
	v_max_f32_e32 v42, 0, v43
	s_nop 1
	v_cvt_pk_bf16_f32 v12, v12, v13
	s_nop 1
	v_cvt_pk_bf16_f32 v13, v14, v15
	v_max_f32_e32 v0, 0, v0
	v_max_f32_e32 v1, 0, v1
	v_max_f32_e32 v2, 0, v2
	v_max_f32_e32 v3, 0, v3
	v_lshl_or_b32 v14, v6, 7, v11
	v_bitop3_b32 v15, v7, v10, 15 bitop3:0x78
	v_mul_f32_e32 v43, v42, v42
	v_mul_f32_e32 v0, v0, v0
	v_mul_f32_e32 v1, v1, v1
	v_mul_f32_e32 v2, v2, v2
	v_mul_f32_e32 v3, v3, v3
	v_lshl_or_b32 v15, v15, 3, v14
	v_bitop3_b32 v16, v7, v6, 4 bitop3:0x36
	v_bitop3_b32 v17, v7, v6, 8 bitop3:0x36
	v_bitop3_b32 v6, v7, v6, 12 bitop3:0x36
	v_mul_f32_e32 v47, v47, v47
	v_mul_f32_e32 v48, v48, v48
	s_nop 1
	v_cvt_pk_bf16_f32 v42, v47, v48
	s_nop 1
	v_cvt_pk_bf16_f32 v43, v49, v43
	s_nop 1
	v_cvt_pk_bf16_f32 v0, v0, v1
	s_nop 1
	v_cvt_pk_bf16_f32 v1, v2, v3
	v_lshl_add_u64 v[2:3], s[4:5], 1, v[128:129]
	v_lshl_or_b32 v16, v16, 3, v14
	v_lshl_or_b32 v17, v17, 3, v14
	v_lshl_or_b32 v6, v6, 3, v14
	ds_write2st64_b64 v15, v[20:21], v[22:23] offset1:4
	ds_write2st64_b64 v16, v[28:29], v[30:31] offset1:4
	ds_write2st64_b64 v17, v[40:41], v[42:43] offset1:4
	ds_write2st64_b64 v6, v[12:13], v[8:9] offset1:4
	ds_write2st64_b64 v15, v[24:25], v[26:27] offset0:8 offset1:12
	ds_write2st64_b64 v16, v[36:37], v[38:39] offset0:8 offset1:12
	ds_write2st64_b64 v17, v[32:33], v[34:35] offset0:8 offset1:12
	ds_write2st64_b64 v6, v[4:5], v[0:1] offset0:8 offset1:12
	v_lshlrev_b32_e32 v4, 4, v10
	v_lshl_add_u64 v[2:3], v[2:3], 0, v[176:177]
	v_and_b32_e32 v0, 8, v10
	v_and_b32_e32 v176, 0x70, v4
	v_bfe_u32 v8, v10, 3, 3
	v_cmp_eq_u32_e32 vcc, 0, v0
	v_lshl_add_u64 v[0:1], v[2:3], 0, v[176:177]
	v_and_b32_e32 v3, 48, v10
	v_lshlrev_b32_e32 v2, 7, v8
	v_bitop3_b32 v9, v4, v3, s9 bitop3:0x6c
	v_or3_b32 v2, v11, v2, v9
	ds_read_b128 v[2:5], v2
	v_lshlrev_b32_e32 v176, 13, v8
	v_or_b32_e32 v12, 8, v8
	s_waitcnt lgkmcnt(0)
	v_cndmask_b32_e32 v7, v3, v5, vcc
	v_cndmask_b32_e32 v6, v2, v4, vcc
	v_cndmask_b32_e32 v5, v5, v3, vcc
	v_cndmask_b32_e32 v4, v4, v2, vcc
	v_lshl_add_u64 v[2:3], v[0:1], 0, v[176:177]
	global_store_dwordx4 v[2:3], v[4:7], off
	v_lshrrev_b32_e32 v3, 1, v12
	v_xor_b32_e32 v3, v3, v10
	v_lshlrev_b32_e32 v3, 4, v3
	v_lshlrev_b32_e32 v2, 7, v12
	v_and_b32_e32 v3, 0x70, v3
	v_or3_b32 v2, v11, v2, v3
	ds_read_b128 v[2:5], v2
	v_lshlrev_b32_e32 v176, 13, v12
	v_or_b32_e32 v12, 16, v8
	s_waitcnt lgkmcnt(0)
	v_cndmask_b32_e32 v7, v3, v5, vcc
	v_cndmask_b32_e32 v6, v2, v4, vcc
	v_cndmask_b32_e32 v5, v5, v3, vcc
	v_cndmask_b32_e32 v4, v4, v2, vcc
	v_lshl_add_u64 v[2:3], v[0:1], 0, v[176:177]
	global_store_dwordx4 v[2:3], v[4:7], off
	v_lshlrev_b32_e32 v2, 7, v12
	v_or3_b32 v2, v11, v2, v9
	ds_read_b128 v[2:5], v2
	v_lshlrev_b32_e32 v176, 13, v12
	v_or_b32_e32 v12, 24, v8
	s_waitcnt lgkmcnt(0)
	v_cndmask_b32_e32 v7, v3, v5, vcc
	v_cndmask_b32_e32 v6, v2, v4, vcc
	v_cndmask_b32_e32 v5, v5, v3, vcc
	v_cndmask_b32_e32 v4, v4, v2, vcc
	v_lshl_add_u64 v[2:3], v[0:1], 0, v[176:177]
	global_store_dwordx4 v[2:3], v[4:7], off
	v_lshrrev_b32_e32 v3, 1, v12
	v_xor_b32_e32 v3, v3, v10
	v_lshlrev_b32_e32 v3, 4, v3
	v_lshlrev_b32_e32 v2, 7, v12
	v_and_b32_e32 v3, 0x70, v3
	v_or3_b32 v2, v11, v2, v3
	ds_read_b128 v[2:5], v2
	v_lshlrev_b32_e32 v176, 13, v12
	v_or_b32_e32 v12, 32, v8
	s_waitcnt lgkmcnt(0)
	v_cndmask_b32_e32 v7, v3, v5, vcc
	v_cndmask_b32_e32 v6, v2, v4, vcc
	v_cndmask_b32_e32 v5, v5, v3, vcc
	v_cndmask_b32_e32 v4, v4, v2, vcc
	v_lshl_add_u64 v[2:3], v[0:1], 0, v[176:177]
	global_store_dwordx4 v[2:3], v[4:7], off
	v_lshlrev_b32_e32 v2, 7, v12
	v_or3_b32 v2, v11, v2, v9
	ds_read_b128 v[2:5], v2
	v_lshlrev_b32_e32 v176, 13, v12
	v_or_b32_e32 v12, 40, v8
	s_waitcnt lgkmcnt(0)
	v_cndmask_b32_e32 v7, v3, v5, vcc
	v_cndmask_b32_e32 v6, v2, v4, vcc
	v_cndmask_b32_e32 v5, v5, v3, vcc
	v_cndmask_b32_e32 v4, v4, v2, vcc
	v_lshl_add_u64 v[2:3], v[0:1], 0, v[176:177]
	global_store_dwordx4 v[2:3], v[4:7], off
	v_lshrrev_b32_e32 v3, 1, v12
	v_xor_b32_e32 v3, v3, v10
	v_lshlrev_b32_e32 v3, 4, v3
	v_lshlrev_b32_e32 v2, 7, v12
	v_and_b32_e32 v3, 0x70, v3
	v_or3_b32 v2, v11, v2, v3
	ds_read_b128 v[2:5], v2
	v_lshlrev_b32_e32 v176, 13, v12
	v_or_b32_e32 v12, 48, v8
	v_or_b32_e32 v8, 56, v8
	s_waitcnt lgkmcnt(0)
	v_cndmask_b32_e32 v7, v3, v5, vcc
	v_cndmask_b32_e32 v6, v2, v4, vcc
	v_cndmask_b32_e32 v5, v5, v3, vcc
	v_cndmask_b32_e32 v4, v4, v2, vcc
	v_lshl_add_u64 v[2:3], v[0:1], 0, v[176:177]
	global_store_dwordx4 v[2:3], v[4:7], off
	v_lshlrev_b32_e32 v2, 7, v12
	v_or3_b32 v2, v11, v2, v9
	ds_read_b128 v[2:5], v2
	v_lshlrev_b32_e32 v176, 13, v12
	s_waitcnt lgkmcnt(0)
	v_cndmask_b32_e32 v7, v3, v5, vcc
	v_cndmask_b32_e32 v6, v2, v4, vcc
	v_cndmask_b32_e32 v5, v5, v3, vcc
	v_cndmask_b32_e32 v4, v4, v2, vcc
	v_lshl_add_u64 v[2:3], v[0:1], 0, v[176:177]
	global_store_dwordx4 v[2:3], v[4:7], off
	v_lshrrev_b32_e32 v3, 1, v8
	v_xor_b32_e32 v3, v3, v10
	v_lshlrev_b32_e32 v3, 4, v3
	v_lshlrev_b32_e32 v2, 7, v8
	v_and_b32_e32 v3, 0x70, v3
	v_or3_b32 v2, v11, v2, v3
	ds_read_b128 v[2:5], v2
	v_lshlrev_b32_e32 v176, 13, v8
	v_lshl_add_u64 v[0:1], v[0:1], 0, v[176:177]
	s_waitcnt lgkmcnt(0)
	v_cndmask_b32_e32 v7, v3, v5, vcc
	v_cndmask_b32_e32 v6, v2, v4, vcc
	v_cndmask_b32_e32 v5, v5, v3, vcc
	v_cndmask_b32_e32 v4, v4, v2, vcc
	global_store_dwordx4 v[0:1], v[4:7], off
	s_cbranch_scc0 .LBB0_183

.Lxk_881:
	ds_read_b128 v[230:233], v140
	ds_read_b128 v[234:237], v140 offset:2048
	ds_read_b128 v[238:241], v140 offset:4096
	ds_read_b128 v[242:245], v140 offset:6144
	ds_read_b128 v[246:249], v141 offset:16384
	ds_read_b128 v[194:197], v141 offset:18432
	ds_read_b128 v[198:201], v141 offset:20480
	ds_read_b128 v[202:205], v141 offset:22528
	s_waitcnt lgkmcnt(8)
	v_mfma_f32_16x16x32_bf16 v[60:63], v[158:161], v[142:145], v[60:63]
	s_add_i32 s0, s0, 2
	v_mfma_f32_16x16x32_bf16 v[56:59], v[162:165], v[142:145], v[56:59]
	s_min_u32 s1, s0, 12
	v_mfma_f32_16x16x32_bf16 v[52:55], v[166:169], v[142:145], v[52:55]
	s_lshl_b32 s56, s1, 7
	v_mfma_f32_16x16x32_bf16 v[48:51], v[170:173], v[142:145], v[48:51]
	s_min_u32 s1, s0, 11
	s_waitcnt vmcnt(15)
	v_mfma_f32_16x16x32_bf16 v[44:47], v[158:161], v[146:149], v[44:47]
	ds_write_b128 v129, v[64:67] offset:32768
	v_mfma_f32_16x16x32_bf16 v[40:43], v[162:165], v[146:149], v[40:43]
	s_waitcnt vmcnt(14)
	v_mfma_f32_16x16x32_bf16 v[36:39], v[166:169], v[146:149], v[36:39]
	ds_write_b128 v129, v[68:71] offset:49152
	v_mfma_f32_16x16x32_bf16 v[32:35], v[170:173], v[146:149], v[32:35]
	s_waitcnt vmcnt(13)
	ds_write_b128 v129, v[72:75] offset:36864
	v_mfma_f32_16x16x32_bf16 v[28:31], v[158:161], v[150:153], v[28:31]
	s_waitcnt vmcnt(12)
	v_mfma_f32_16x16x32_bf16 v[24:27], v[162:165], v[150:153], v[24:27]
	ds_write_b128 v129, v[76:79] offset:53248
	v_mfma_f32_16x16x32_bf16 v[20:23], v[166:169], v[150:153], v[20:23]
	s_waitcnt vmcnt(11)
	v_mfma_f32_16x16x32_bf16 v[16:19], v[170:173], v[150:153], v[16:19]
	ds_write_b128 v129, v[80:83] offset:40960
	s_waitcnt vmcnt(10)
	v_mfma_f32_16x16x32_bf16 v[12:15], v[158:161], v[154:157], v[12:15]
	ds_write_b128 v129, v[84:87] offset:57344
	v_mfma_f32_16x16x32_bf16 v[8:11], v[162:165], v[154:157], v[8:11]
	s_waitcnt vmcnt(9)
	v_mfma_f32_16x16x32_bf16 v[4:7], v[166:169], v[154:157], v[4:7]
	ds_write_b128 v129, v[88:91] offset:45056
	v_mfma_f32_16x16x32_bf16 v[0:3], v[170:173], v[154:157], v[0:3]
	s_waitcnt vmcnt(8)
	ds_write_b128 v129, v[92:95] offset:61440
	s_waitcnt lgkmcnt(0)
	s_barrier
	ds_read_b128 v[142:145], v138 offset:32768
	ds_read_b128 v[146:149], v138 offset:34816
	ds_read_b128 v[150:153], v138 offset:36864
	ds_read_b128 v[154:157], v138 offset:38912
	ds_read_b128 v[158:161], v139 offset:49152
	ds_read_b128 v[162:165], v139 offset:51200
	ds_read_b128 v[166:169], v139 offset:53248
	ds_read_b128 v[170:173], v139 offset:55296
	v_mfma_f32_16x16x32_bf16 v[60:63], v[246:249], v[230:233], v[60:63]
	v_lshl_add_u64 v[88:89], v[134:135], 0, s[56:57]
	v_mfma_f32_16x16x32_bf16 v[56:59], v[194:197], v[230:233], v[56:59]
	v_add_co_u32_e32 v72, vcc, s65, v88
	v_lshl_add_u64 v[92:93], v[136:137], 0, s[56:57]
	v_mfma_f32_16x16x32_bf16 v[52:55], v[198:201], v[230:233], v[52:55]
	s_nop 0
	v_mfma_f32_16x16x32_bf16 v[48:51], v[202:205], v[230:233], v[48:51]
	v_addc_co_u32_e32 v73, vcc, 0, v89, vcc
	v_add_co_u32_e32 v76, vcc, s65, v92
	v_mfma_f32_16x16x32_bf16 v[44:47], v[246:249], v[234:237], v[44:47]
	global_load_dwordx4 v[64:67], v[88:89], off offset:384
	v_mfma_f32_16x16x32_bf16 v[40:43], v[194:197], v[234:237], v[40:43]
	global_load_dwordx4 v[68:71], v[92:93], off offset:384
	v_addc_co_u32_e32 v77, vcc, 0, v93, vcc
	v_mfma_f32_16x16x32_bf16 v[36:39], v[198:201], v[234:237], v[36:39]
	v_add_co_u32_e32 v80, vcc, s46, v88
	v_mfma_f32_16x16x32_bf16 v[32:35], v[202:205], v[234:237], v[32:35]
	s_nop 0
	v_addc_co_u32_e32 v81, vcc, 0, v89, vcc
	v_add_co_u32_e32 v84, vcc, s46, v92
	v_mfma_f32_16x16x32_bf16 v[28:31], v[246:249], v[238:241], v[28:31]
	s_nop 0
	v_addc_co_u32_e32 v85, vcc, 0, v93, vcc
	v_add_co_u32_e32 v88, vcc, s47, v88
	v_mfma_f32_16x16x32_bf16 v[24:27], v[194:197], v[238:241], v[24:27]
	s_nop 0
	v_addc_co_u32_e32 v89, vcc, 0, v89, vcc
	v_mfma_f32_16x16x32_bf16 v[20:23], v[198:201], v[238:241], v[20:23]
	v_add_co_u32_e32 v92, vcc, s47, v92
	s_nop 1
	v_addc_co_u32_e32 v93, vcc, 0, v93, vcc
	v_mfma_f32_16x16x32_bf16 v[16:19], v[202:205], v[238:241], v[16:19]
	global_load_dwordx4 v[72:75], v[72:73], off offset:384
	v_mfma_f32_16x16x32_bf16 v[12:15], v[246:249], v[242:245], v[12:15]
	global_load_dwordx4 v[76:79], v[76:77], off offset:384
	s_lshl_b32 s56, s1, 7
	v_mfma_f32_16x16x32_bf16 v[8:11], v[194:197], v[242:245], v[8:11]
	global_load_dwordx4 v[80:83], v[80:81], off offset:384
	v_mfma_f32_16x16x32_bf16 v[4:7], v[198:201], v[242:245], v[4:7]
	global_load_dwordx4 v[84:87], v[84:85], off offset:384
	s_cmp_lt_u32 s0, 14
	v_mfma_f32_16x16x32_bf16 v[0:3], v[202:205], v[242:245], v[0:3]
	global_load_dwordx4 v[88:91], v[88:89], off offset:384
	global_load_dwordx4 v[92:95], v[92:93], off offset:384
	ds_read_b128 v[230:233], v140 offset:32768
	ds_read_b128 v[234:237], v140 offset:34816
	ds_read_b128 v[238:241], v140 offset:36864
	ds_read_b128 v[242:245], v140 offset:38912
	ds_read_b128 v[246:249], v141 offset:49152
	ds_read_b128 v[194:197], v141 offset:51200
	ds_read_b128 v[198:201], v141 offset:53248
	ds_read_b128 v[202:205], v141 offset:55296
	s_waitcnt lgkmcnt(8)
	v_mfma_f32_16x16x32_bf16 v[60:63], v[158:161], v[142:145], v[60:63]
	s_waitcnt vmcnt(15)
	v_mfma_f32_16x16x32_bf16 v[56:59], v[162:165], v[142:145], v[56:59]
	ds_write_b128 v129, v[96:99]
	v_mfma_f32_16x16x32_bf16 v[52:55], v[166:169], v[142:145], v[52:55]
	s_waitcnt vmcnt(14)
	v_mfma_f32_16x16x32_bf16 v[48:51], v[170:173], v[142:145], v[48:51]
	ds_write_b128 v129, v[100:103] offset:16384
	v_mfma_f32_16x16x32_bf16 v[44:47], v[158:161], v[146:149], v[44:47]
	s_waitcnt vmcnt(13)
	v_mfma_f32_16x16x32_bf16 v[40:43], v[162:165], v[146:149], v[40:43]
	ds_write_b128 v129, v[104:107] offset:4096
	v_mfma_f32_16x16x32_bf16 v[36:39], v[166:169], v[146:149], v[36:39]
	s_waitcnt vmcnt(12)
	v_mfma_f32_16x16x32_bf16 v[32:35], v[170:173], v[146:149], v[32:35]
	ds_write_b128 v129, v[108:111] offset:20480
	v_mfma_f32_16x16x32_bf16 v[28:31], v[158:161], v[150:153], v[28:31]
	s_waitcnt vmcnt(11)
	v_mfma_f32_16x16x32_bf16 v[24:27], v[162:165], v[150:153], v[24:27]
	ds_write_b128 v129, v[112:115] offset:8192
	v_mfma_f32_16x16x32_bf16 v[20:23], v[166:169], v[150:153], v[20:23]
	s_waitcnt vmcnt(10)
	v_mfma_f32_16x16x32_bf16 v[16:19], v[170:173], v[150:153], v[16:19]
	ds_write_b128 v129, v[116:119] offset:24576
	v_mfma_f32_16x16x32_bf16 v[12:15], v[158:161], v[154:157], v[12:15]
	s_waitcnt vmcnt(9)
	v_mfma_f32_16x16x32_bf16 v[8:11], v[162:165], v[154:157], v[8:11]
	ds_write_b128 v129, v[120:123] offset:12288
	v_mfma_f32_16x16x32_bf16 v[4:7], v[166:169], v[154:157], v[4:7]
	s_waitcnt vmcnt(8)
	v_mfma_f32_16x16x32_bf16 v[0:3], v[170:173], v[154:157], v[0:3]
	ds_write_b128 v129, v[124:127] offset:28672
	s_waitcnt lgkmcnt(0)
	s_barrier
	ds_read_b128 v[142:145], v138
	ds_read_b128 v[146:149], v138 offset:2048
	ds_read_b128 v[150:153], v138 offset:4096
	ds_read_b128 v[154:157], v138 offset:6144
	ds_read_b128 v[158:161], v139 offset:16384
	ds_read_b128 v[162:165], v139 offset:18432
	ds_read_b128 v[166:169], v139 offset:20480
	ds_read_b128 v[170:173], v139 offset:22528
	v_mfma_f32_16x16x32_bf16 v[60:63], v[246:249], v[230:233], v[60:63]
	v_lshl_add_u64 v[120:121], v[134:135], 0, s[56:57]
	v_mfma_f32_16x16x32_bf16 v[56:59], v[194:197], v[230:233], v[56:59]
	v_add_co_u32_e32 v104, vcc, s65, v120
	v_lshl_add_u64 v[124:125], v[136:137], 0, s[56:57]
	v_mfma_f32_16x16x32_bf16 v[52:55], v[198:201], v[230:233], v[52:55]
	s_nop 0
	v_addc_co_u32_e32 v105, vcc, 0, v121, vcc
	v_mfma_f32_16x16x32_bf16 v[48:51], v[202:205], v[230:233], v[48:51]
	v_add_co_u32_e32 v108, vcc, s65, v124
	v_mfma_f32_16x16x32_bf16 v[44:47], v[246:249], v[234:237], v[44:47]
	global_load_dwordx4 v[96:99], v[120:121], off offset:512
	global_load_dwordx4 v[100:103], v[124:125], off offset:512
	v_mfma_f32_16x16x32_bf16 v[40:43], v[194:197], v[234:237], v[40:43]
	v_addc_co_u32_e32 v109, vcc, 0, v125, vcc
	v_add_co_u32_e32 v112, vcc, s46, v120
	v_mfma_f32_16x16x32_bf16 v[36:39], v[198:201], v[234:237], v[36:39]
	global_load_dwordx4 v[104:107], v[104:105], off offset:512
	v_mfma_f32_16x16x32_bf16 v[32:35], v[202:205], v[234:237], v[32:35]
	s_nop 0
	v_addc_co_u32_e32 v113, vcc, 0, v121, vcc
	v_mfma_f32_16x16x32_bf16 v[28:31], v[246:249], v[238:241], v[28:31]
	v_add_co_u32_e32 v116, vcc, s46, v124
	global_load_dwordx4 v[108:111], v[108:109], off offset:512
	v_mfma_f32_16x16x32_bf16 v[24:27], v[194:197], v[238:241], v[24:27]
	s_nop 0
	v_mfma_f32_16x16x32_bf16 v[20:23], v[198:201], v[238:241], v[20:23]
	v_addc_co_u32_e32 v117, vcc, 0, v125, vcc
	v_add_co_u32_e32 v120, vcc, s47, v120
	v_mfma_f32_16x16x32_bf16 v[16:19], v[202:205], v[238:241], v[16:19]
	global_load_dwordx4 v[112:115], v[112:113], off offset:512
	s_nop 0
	v_mfma_f32_16x16x32_bf16 v[12:15], v[246:249], v[242:245], v[12:15]
	v_addc_co_u32_e32 v121, vcc, 0, v121, vcc
	v_mfma_f32_16x16x32_bf16 v[8:11], v[194:197], v[242:245], v[8:11]
	v_add_co_u32_e32 v124, vcc, s47, v124
	global_load_dwordx4 v[116:119], v[116:117], off offset:512
	v_mfma_f32_16x16x32_bf16 v[4:7], v[198:201], v[242:245], v[4:7]
	s_nop 0
	v_addc_co_u32_e32 v125, vcc, 0, v125, vcc
	v_mfma_f32_16x16x32_bf16 v[0:3], v[202:205], v[242:245], v[0:3]
	global_load_dwordx4 v[120:123], v[120:121], off offset:512
	global_load_dwordx4 v[124:127], v[124:125], off offset:512
	s_cbranch_scc1 .Lxk_881
	s_waitcnt vmcnt(0) lgkmcnt(0)
	v_mov_b32_e32 v194, 0x11004
	v_mov_b32_e32 v195, 1
	v_mov_b32_e32 v196, 0x3727c5ac
	v_mov_b32_e32 v197, 0x260
	v_mov_b32_e32 v198, -1
	v_mbcnt_lo_u32_b32 v199, -1, 0
	v_mbcnt_hi_u32_b32 v199, -1, v199
	v_and_b32_e32 v200, 64, v199
	v_add_u32_e32 v201, 64, v200
	v_xor_b32_e32 v202, 32, v199
	v_xor_b32_e32 v203, 16, v199
	v_xor_b32_e32 v204, 8, v199
	v_xor_b32_e32 v205, 4, v199
	s_cmp_lt_i32 s16, 16
	s_waitcnt vmcnt(15)
	v_mov_b32_e32 v64, v192
	s_cselect_b64 s[0:1], -1, 0
	s_cmp_gt_i32 s16, 15
	s_cselect_b64 s[12:13], -1, 0
	s_waitcnt vmcnt(14)
	v_bfe_u32 v70, v64, 6, 1
	s_and_b64 vcc, exec, s[0:1]
	s_cbranch_vccnz .LBB0_933
	s_sub_i32 s0, s16, 18
	s_cmp_gt_u32 s0, 3
	s_mov_b64 s[0:1], -1
	s_cbranch_scc0 .LBB0_933
	s_cmp_gt_u32 s16, 21
	s_cselect_b64 s[0:1], -1, 0
	s_cmp_gt_u32 s16, 17
	v_bfe_u32 v65, v64, 4, 2
	v_and_or_b32 v66, v64, 15, v128
	s_cselect_b64 s[14:15], -1, 0
	v_cndmask_b32_e64 v64, 0, 1, s[0:1]
	v_cmp_ne_u32_e64 s[40:41], 0, v70
	v_cmp_gt_u32_e64 s[38:39], 2, v65
	v_lshlrev_b32_e32 v71, 2, v65
	v_ashrrev_i32_e32 v67, 31, v66
	s_mov_b64 s[4:5], -1
	s_and_b64 vcc, exec, s[14:15]
	v_cmp_ne_u32_e64 s[0:1], 1, v64
	s_cbranch_vccz .LBB0_894
	s_and_b64 vcc, exec, s[0:1]
	s_cbranch_vccnz .LBB0_893
	s_and_saveexec_b64 s[4:5], s[40:41]
	s_xor_b64 s[4:5], exec, s[4:5]
	s_cbranch_execz .LBB0_890
	s_and_saveexec_b64 s[18:19], s[38:39]
	s_cbranch_execz .LBB0_889
	v_lshlrev_b64 v[64:65], 5, v[66:67]
	v_lshl_add_u64 v[64:65], s[10:11], 0, v[64:65]
	v_lshlrev_b32_e32 v176, 2, v71
	s_mov_b32 s22, 0x3d3504f3
	v_lshl_add_u64 v[64:65], v[64:65], 0, v[176:177]
	s_waitcnt vmcnt(13)
	v_pk_mul_f32 v[74:75], v[62:63], s[22:23] op_sel_hi:[1,0]
	v_pk_mul_f32 v[72:73], v[60:61], s[22:23] op_sel_hi:[1,0]
	global_store_dwordx4 v[64:65], v[72:75], off

.Lxk_1422:
	ds_read_b128 v[230:233], v137
	ds_read_b128 v[234:237], v137 offset:2048
	ds_read_b128 v[238:241], v137 offset:4096
	ds_read_b128 v[242:245], v137 offset:6144
	ds_read_b128 v[246:249], v138 offset:16384
	ds_read_b128 v[194:197], v138 offset:18432
	ds_read_b128 v[198:201], v138 offset:20480
	ds_read_b128 v[202:205], v138 offset:22528
	s_waitcnt lgkmcnt(8)
	v_mfma_f32_16x16x32_bf16 v[124:127], v[156:159], v[140:143], v[124:127]
	s_add_i32 s0, s0, 2
	v_mfma_f32_16x16x32_bf16 v[120:123], v[160:163], v[140:143], v[120:123]
	s_min_u32 s1, s0, 12
	v_mfma_f32_16x16x32_bf16 v[112:115], v[164:167], v[140:143], v[112:115]
	s_lshl_b32 s56, s1, 7
	v_mfma_f32_16x16x32_bf16 v[96:99], v[168:171], v[140:143], v[96:99]
	s_min_u32 s1, s0, 11
	s_waitcnt vmcnt(15)
	v_mfma_f32_16x16x32_bf16 v[76:79], v[156:159], v[144:147], v[76:79]
	ds_write_b128 v134, v[40:43] offset:32768
	v_mfma_f32_16x16x32_bf16 v[52:55], v[160:163], v[144:147], v[52:55]
	s_waitcnt vmcnt(14)
	v_mfma_f32_16x16x32_bf16 v[36:39], v[164:167], v[144:147], v[36:39]
	ds_write_b128 v134, v[44:47] offset:49152
	v_mfma_f32_16x16x32_bf16 v[32:35], v[168:171], v[144:147], v[32:35]
	s_waitcnt vmcnt(13)
	ds_write_b128 v134, v[48:51] offset:36864
	v_mfma_f32_16x16x32_bf16 v[28:31], v[156:159], v[148:151], v[28:31]
	s_waitcnt vmcnt(12)
	v_mfma_f32_16x16x32_bf16 v[24:27], v[160:163], v[148:151], v[24:27]
	ds_write_b128 v134, v[56:59] offset:53248
	v_mfma_f32_16x16x32_bf16 v[20:23], v[164:167], v[148:151], v[20:23]
	s_waitcnt vmcnt(11)
	v_mfma_f32_16x16x32_bf16 v[16:19], v[168:171], v[148:151], v[16:19]
	ds_write_b128 v134, v[60:63] offset:40960
	s_waitcnt vmcnt(10)
	v_mfma_f32_16x16x32_bf16 v[12:15], v[156:159], v[152:155], v[12:15]
	ds_write_b128 v134, v[64:67] offset:57344
	v_mfma_f32_16x16x32_bf16 v[8:11], v[160:163], v[152:155], v[8:11]
	s_waitcnt vmcnt(9)
	v_mfma_f32_16x16x32_bf16 v[4:7], v[164:167], v[152:155], v[4:7]
	ds_write_b128 v134, v[68:71] offset:45056
	v_mfma_f32_16x16x32_bf16 v[0:3], v[168:171], v[152:155], v[0:3]
	s_waitcnt vmcnt(8)
	ds_write_b128 v134, v[72:75] offset:61440
	s_waitcnt lgkmcnt(0)
	s_barrier
	ds_read_b128 v[140:143], v135 offset:32768
	ds_read_b128 v[144:147], v135 offset:34816
	ds_read_b128 v[148:151], v135 offset:36864
	ds_read_b128 v[152:155], v135 offset:38912
	ds_read_b128 v[156:159], v136 offset:49152
	ds_read_b128 v[160:163], v136 offset:51200
	ds_read_b128 v[164:167], v136 offset:53248
	ds_read_b128 v[168:171], v136 offset:55296
	v_mfma_f32_16x16x32_bf16 v[124:127], v[246:249], v[230:233], v[124:127]
	v_lshl_add_u64 v[68:69], v[130:131], 0, s[56:57]
	v_mfma_f32_16x16x32_bf16 v[120:123], v[194:197], v[230:233], v[120:123]
	v_add_co_u32_e32 v48, vcc, s65, v68
	v_lshl_add_u64 v[72:73], v[132:133], 0, s[56:57]
	v_mfma_f32_16x16x32_bf16 v[112:115], v[198:201], v[230:233], v[112:115]
	s_nop 0
	v_mfma_f32_16x16x32_bf16 v[96:99], v[202:205], v[230:233], v[96:99]
	v_addc_co_u32_e32 v49, vcc, 0, v69, vcc
	v_add_co_u32_e32 v56, vcc, s65, v72
	v_mfma_f32_16x16x32_bf16 v[76:79], v[246:249], v[234:237], v[76:79]
	global_load_dwordx4 v[40:43], v[68:69], off offset:384
	v_mfma_f32_16x16x32_bf16 v[52:55], v[194:197], v[234:237], v[52:55]
	global_load_dwordx4 v[44:47], v[72:73], off offset:384
	v_addc_co_u32_e32 v57, vcc, 0, v73, vcc
	v_mfma_f32_16x16x32_bf16 v[36:39], v[198:201], v[234:237], v[36:39]
	v_add_co_u32_e32 v60, vcc, s46, v68
	v_mfma_f32_16x16x32_bf16 v[32:35], v[202:205], v[234:237], v[32:35]
	s_nop 0
	v_addc_co_u32_e32 v61, vcc, 0, v69, vcc
	v_add_co_u32_e32 v64, vcc, s46, v72
	v_mfma_f32_16x16x32_bf16 v[28:31], v[246:249], v[238:241], v[28:31]
	s_nop 0
	v_addc_co_u32_e32 v65, vcc, 0, v73, vcc
	v_add_co_u32_e32 v68, vcc, s47, v68
	v_mfma_f32_16x16x32_bf16 v[24:27], v[194:197], v[238:241], v[24:27]
	s_nop 0
	v_addc_co_u32_e32 v69, vcc, 0, v69, vcc
	v_mfma_f32_16x16x32_bf16 v[20:23], v[198:201], v[238:241], v[20:23]
	v_add_co_u32_e32 v72, vcc, s47, v72
	s_nop 1
	v_addc_co_u32_e32 v73, vcc, 0, v73, vcc
	v_mfma_f32_16x16x32_bf16 v[16:19], v[202:205], v[238:241], v[16:19]
	global_load_dwordx4 v[48:51], v[48:49], off offset:384
	v_mfma_f32_16x16x32_bf16 v[12:15], v[246:249], v[242:245], v[12:15]
	global_load_dwordx4 v[56:59], v[56:57], off offset:384
	s_lshl_b32 s56, s1, 7
	v_mfma_f32_16x16x32_bf16 v[8:11], v[194:197], v[242:245], v[8:11]
	global_load_dwordx4 v[60:63], v[60:61], off offset:384
	v_mfma_f32_16x16x32_bf16 v[4:7], v[198:201], v[242:245], v[4:7]
	global_load_dwordx4 v[64:67], v[64:65], off offset:384
	s_cmp_lt_u32 s0, 14
	v_mfma_f32_16x16x32_bf16 v[0:3], v[202:205], v[242:245], v[0:3]
	global_load_dwordx4 v[68:71], v[68:69], off offset:384
	global_load_dwordx4 v[72:75], v[72:73], off offset:384
	ds_read_b128 v[230:233], v137 offset:32768
	ds_read_b128 v[234:237], v137 offset:34816
	ds_read_b128 v[238:241], v137 offset:36864
	ds_read_b128 v[242:245], v137 offset:38912
	ds_read_b128 v[246:249], v138 offset:49152
	ds_read_b128 v[194:197], v138 offset:51200
	ds_read_b128 v[198:201], v138 offset:53248
	ds_read_b128 v[202:205], v138 offset:55296
	s_waitcnt lgkmcnt(8)
	v_mfma_f32_16x16x32_bf16 v[124:127], v[156:159], v[140:143], v[124:127]
	s_waitcnt vmcnt(15)
	v_mfma_f32_16x16x32_bf16 v[120:123], v[160:163], v[140:143], v[120:123]
	ds_write_b128 v134, v[80:83]
	v_mfma_f32_16x16x32_bf16 v[112:115], v[164:167], v[140:143], v[112:115]
	s_waitcnt vmcnt(14)
	v_mfma_f32_16x16x32_bf16 v[96:99], v[168:171], v[140:143], v[96:99]
	ds_write_b128 v134, v[84:87] offset:16384
	v_mfma_f32_16x16x32_bf16 v[76:79], v[156:159], v[144:147], v[76:79]
	s_waitcnt vmcnt(13)
	v_mfma_f32_16x16x32_bf16 v[52:55], v[160:163], v[144:147], v[52:55]
	ds_write_b128 v134, v[88:91] offset:4096
	v_mfma_f32_16x16x32_bf16 v[36:39], v[164:167], v[144:147], v[36:39]
	s_waitcnt vmcnt(12)
	v_mfma_f32_16x16x32_bf16 v[32:35], v[168:171], v[144:147], v[32:35]
	ds_write_b128 v134, v[92:95] offset:20480
	v_mfma_f32_16x16x32_bf16 v[28:31], v[156:159], v[148:151], v[28:31]
	s_waitcnt vmcnt(11)
	v_mfma_f32_16x16x32_bf16 v[24:27], v[160:163], v[148:151], v[24:27]
	ds_write_b128 v134, v[100:103] offset:8192
	v_mfma_f32_16x16x32_bf16 v[20:23], v[164:167], v[148:151], v[20:23]
	s_waitcnt vmcnt(10)
	v_mfma_f32_16x16x32_bf16 v[16:19], v[168:171], v[148:151], v[16:19]
	ds_write_b128 v134, v[104:107] offset:24576
	v_mfma_f32_16x16x32_bf16 v[12:15], v[156:159], v[152:155], v[12:15]
	s_waitcnt vmcnt(9)
	v_mfma_f32_16x16x32_bf16 v[8:11], v[160:163], v[152:155], v[8:11]
	ds_write_b128 v134, v[108:111] offset:12288
	v_mfma_f32_16x16x32_bf16 v[4:7], v[164:167], v[152:155], v[4:7]
	s_waitcnt vmcnt(8)
	v_mfma_f32_16x16x32_bf16 v[0:3], v[168:171], v[152:155], v[0:3]
	ds_write_b128 v134, v[116:119] offset:28672
	s_waitcnt lgkmcnt(0)
	s_barrier
	ds_read_b128 v[140:143], v135
	ds_read_b128 v[144:147], v135 offset:2048
	ds_read_b128 v[148:151], v135 offset:4096
	ds_read_b128 v[152:155], v135 offset:6144
	ds_read_b128 v[156:159], v136 offset:16384
	ds_read_b128 v[160:163], v136 offset:18432
	ds_read_b128 v[164:167], v136 offset:20480
	ds_read_b128 v[168:171], v136 offset:22528
	v_mfma_f32_16x16x32_bf16 v[124:127], v[246:249], v[230:233], v[124:127]
	v_lshl_add_u64 v[108:109], v[130:131], 0, s[56:57]
	v_mfma_f32_16x16x32_bf16 v[120:123], v[194:197], v[230:233], v[120:123]
	v_add_co_u32_e32 v88, vcc, s65, v108
	v_lshl_add_u64 v[116:117], v[132:133], 0, s[56:57]
	v_mfma_f32_16x16x32_bf16 v[112:115], v[198:201], v[230:233], v[112:115]
	s_nop 0
	v_addc_co_u32_e32 v89, vcc, 0, v109, vcc
	v_mfma_f32_16x16x32_bf16 v[96:99], v[202:205], v[230:233], v[96:99]
	v_add_co_u32_e32 v92, vcc, s65, v116
	v_mfma_f32_16x16x32_bf16 v[76:79], v[246:249], v[234:237], v[76:79]
	global_load_dwordx4 v[80:83], v[108:109], off offset:512
	global_load_dwordx4 v[84:87], v[116:117], off offset:512
	v_mfma_f32_16x16x32_bf16 v[52:55], v[194:197], v[234:237], v[52:55]
	v_addc_co_u32_e32 v93, vcc, 0, v117, vcc
	v_add_co_u32_e32 v100, vcc, s46, v108
	v_mfma_f32_16x16x32_bf16 v[36:39], v[198:201], v[234:237], v[36:39]
	global_load_dwordx4 v[88:91], v[88:89], off offset:512
	v_mfma_f32_16x16x32_bf16 v[32:35], v[202:205], v[234:237], v[32:35]
	s_nop 0
	v_addc_co_u32_e32 v101, vcc, 0, v109, vcc
	v_mfma_f32_16x16x32_bf16 v[28:31], v[246:249], v[238:241], v[28:31]
	v_add_co_u32_e32 v104, vcc, s46, v116
	global_load_dwordx4 v[92:95], v[92:93], off offset:512
	v_mfma_f32_16x16x32_bf16 v[24:27], v[194:197], v[238:241], v[24:27]
	s_nop 0
	v_mfma_f32_16x16x32_bf16 v[20:23], v[198:201], v[238:241], v[20:23]
	v_addc_co_u32_e32 v105, vcc, 0, v117, vcc
	v_add_co_u32_e32 v108, vcc, s47, v108
	v_mfma_f32_16x16x32_bf16 v[16:19], v[202:205], v[238:241], v[16:19]
	global_load_dwordx4 v[100:103], v[100:101], off offset:512
	s_nop 0
	v_mfma_f32_16x16x32_bf16 v[12:15], v[246:249], v[242:245], v[12:15]
	v_addc_co_u32_e32 v109, vcc, 0, v109, vcc
	v_mfma_f32_16x16x32_bf16 v[8:11], v[194:197], v[242:245], v[8:11]
	v_add_co_u32_e32 v116, vcc, s47, v116
	global_load_dwordx4 v[104:107], v[104:105], off offset:512
	v_mfma_f32_16x16x32_bf16 v[4:7], v[198:201], v[242:245], v[4:7]
	s_nop 0
	v_addc_co_u32_e32 v117, vcc, 0, v117, vcc
	v_mfma_f32_16x16x32_bf16 v[0:3], v[202:205], v[242:245], v[0:3]
	global_load_dwordx4 v[108:111], v[108:109], off offset:512
	global_load_dwordx4 v[116:119], v[116:117], off offset:512
	s_cbranch_scc1 .Lxk_1422
	s_waitcnt vmcnt(0) lgkmcnt(0)
	v_mov_b32_e32 v194, 0x11004
	v_mov_b32_e32 v195, 1
	v_mov_b32_e32 v196, 0x3727c5ac
	v_mov_b32_e32 v197, 0x260
	v_mov_b32_e32 v198, -1
	v_mbcnt_lo_u32_b32 v199, -1, 0
	v_mbcnt_hi_u32_b32 v199, -1, v199
	v_and_b32_e32 v200, 64, v199
	v_add_u32_e32 v201, 64, v200
	v_xor_b32_e32 v202, 32, v199
	v_xor_b32_e32 v203, 16, v199
	v_xor_b32_e32 v204, 8, v199
	v_xor_b32_e32 v205, 4, v199
	s_cmp_gt_i32 s2, 9
	s_waitcnt vmcnt(12)
	v_mov_b32_e32 v56, v192
	s_cselect_b64 s[0:1], -1, 0
	s_cmp_lt_i32 s2, 10
	s_cbranch_scc1 .LBB0_1425
	v_mul_f32_e32 v40, 0x3d372713, v124
	v_mul_f32_e32 v41, 0x3d372713, v125
	v_mul_f32_e32 v42, 0x3d372713, v126
	v_mul_f32_e32 v43, 0x3d372713, v127
	v_mul_f32_e32 v40, v124, v40
	v_mul_f32_e32 v41, v125, v41
	v_mul_f32_e32 v42, v126, v42
	v_mul_f32_e32 v43, v127, v43
	v_fma_f32 v40, v124, v40, v124
	v_fma_f32 v41, v125, v41, v125
	v_fma_f32 v42, v126, v42, v126
	v_fma_f32 v43, v127, v43, v127
	v_mul_f32_e32 v40, 0x3f4c422a, v40
	v_mul_f32_e32 v41, 0x3f4c422a, v41
	v_mul_f32_e32 v42, 0x3f4c422a, v42
	v_mul_f32_e32 v43, 0x3f4c422a, v43
	v_add_f32_e32 v40, v40, v40
	v_add_f32_e32 v41, v41, v41
	v_add_f32_e32 v42, v42, v42
	v_add_f32_e32 v43, v43, v43
	v_mul_f32_e32 v40, 0x3fb8aa3b, v40
	v_mul_f32_e32 v41, 0x3fb8aa3b, v41
	v_mul_f32_e32 v42, 0x3fb8aa3b, v42
	v_mul_f32_e32 v43, 0x3fb8aa3b, v43
	v_exp_f32_e32 v40, v40
	v_exp_f32_e32 v41, v41
	v_exp_f32_e32 v42, v42
	v_exp_f32_e32 v43, v43
	v_add_f32_e32 v40, 1.0, v40
	v_add_f32_e32 v41, 1.0, v41
	v_add_f32_e32 v42, 1.0, v42
	v_add_f32_e32 v43, 1.0, v43
	v_rcp_f32_e32 v40, v40
	v_rcp_f32_e32 v42, v42
	v_rcp_f32_e32 v43, v43
	v_rcp_f32_e32 v41, v41
	v_pk_mul_f32 v[44:45], v[126:127], 0.5 op_sel_hi:[1,0]
	v_pk_mul_f32 v[46:47], v[124:125], 0.5 op_sel_hi:[1,0]
	v_pk_fma_f32 v[42:43], v[42:43], -2.0, 1.0 op_sel_hi:[1,0,0]
	v_pk_fma_f32 v[40:41], v[40:41], -2.0, 1.0 op_sel_hi:[1,0,0]
	v_pk_add_f32 v[42:43], v[42:43], 1.0 op_sel_hi:[1,0]
	v_pk_add_f32 v[40:41], v[40:41], 1.0 op_sel_hi:[1,0]
	v_pk_mul_f32 v[126:127], v[44:45], v[42:43]
	v_pk_mul_f32 v[124:125], v[46:47], v[40:41]
